# v43 + second panel-counter prefetch for the workgroups that ran a thin unit after their signal (read before the thin unit's closing drain, complete means >= 4; v255 zeroed at every phase end)
# speedup vs baseline: 1.0116x; 1.0115x over previous
.LBB0_583:
	s_mov_b64 s[100:101], exec
	v_readlane_b32 s98, v251, 41
	v_readlane_b32 s99, v251, 42
	s_and_b64 s[98:99], s[100:101], s[98:99]
	s_mov_b64 exec, s[98:99]
	s_cbranch_execz .Lmy_pm3_skip
	v_readlane_b32 s98, v251, 62
	v_readlane_b32 s99, v251, 61
	s_lshl_b32 s98, s98, 3
	s_and_b32 s99, s99, 7
	s_or_b32 s98, s98, s99
	s_lshl_b32 s98, s98, 8
	v_mov_b32_e32 v252, s98
	v_readlane_b32 s98, v251, 20
	v_readlane_b32 s99, v251, 21
	s_add_u32 s98, s98, 0x18000
	s_addc_u32 s99, s99, 0
	global_load_dword v254, v252, s[98:99] sc1
	v_mov_b32_e32 v255, 0

.LBB0_590:
	s_or_b64 exec, exec, s[4:5]
	s_barrier
	s_mov_b64 s[100:101], exec
	v_readlane_b32 s98, v251, 41
	v_readlane_b32 s99, v251, 42
	s_and_b64 s[98:99], s[100:101], s[98:99]
	s_mov_b64 exec, s[98:99]
	s_cbranch_execz .Lmy_pn3_skip
	v_readlane_b32 s98, v251, 62
	v_readlane_b32 s99, v251, 61
	s_lshl_b32 s98, s98, 3
	s_and_b32 s99, s99, 7
	s_or_b32 s98, s98, s99
	s_lshl_b32 s98, s98, 8
	v_mov_b32_e32 v252, s98
	v_readlane_b32 s98, v251, 20
	v_readlane_b32 s99, v251, 21
	s_add_u32 s98, s98, 0x18000
	s_addc_u32 s99, s99, 0
	global_load_dword v255, v252, s[98:99] sc1
.Lmy_pn3_skip:
	s_mov_b64 exec, s[100:101]
	s_waitcnt vmcnt(0)
	s_barrier
	s_mov_b64 s[2:3], exec
	v_readlane_b32 s4, v251, 41
	v_readlane_b32 s5, v251, 42
	s_and_b64 s[4:5], s[2:3], s[4:5]
	s_mov_b64 exec, s[4:5]
	s_cbranch_execz .LBB0_593
	s_mov_b64 s[4:5], exec
	v_mbcnt_lo_u32_b32 v2, s4, 0
	v_mbcnt_hi_u32_b32 v2, s5, v2
	v_cmp_eq_u32_e32 vcc, 0, v2
	s_and_b64 s[18:19], exec, vcc
	s_mov_b64 exec, s[18:19]
	s_cbranch_execz .LBB0_593
	s_bcnt1_i32_b64 s1, s[4:5]
	v_mov_b32_e32 v2, 0
	v_mov_b32_e32 v3, s1
	global_atomic_add v2, v3, s[14:15]

.LBB0_594:
	v_readlane_b32 s36, v251, 6
	v_readlane_b32 s48, v251, 18
	v_readlane_b32 s49, v251, 19
	s_add_u32 s28, s6, 0x4000
	v_readlane_b32 s50, v251, 20
	v_readlane_b32 s51, v251, 21
	s_mov_b64 s[20:21], s[48:49]
	s_addc_u32 s29, s7, 0
	s_mov_b64 s[22:23], s[50:51]
	s_add_u32 s20, s22, 0x28100
	s_addc_u32 s21, s23, 0
	s_add_u32 s22, s22, 0x13800000
	s_addc_u32 s23, s23, 0
	s_cmp_lt_i32 s72, 5
	s_cselect_b64 s[2:3], -1, 0
	s_cmp_gt_i32 s73, 4
	s_cselect_b64 s[4:5], -1, 0
	s_and_b64 s[2:3], s[2:3], s[4:5]
	s_andn2_b64 vcc, exec, s[2:3]
	v_cmp_gt_u32_e64 s[2:3], 64, v0
	v_readlane_b32 s75, v251, 62
	v_readlane_b32 s37, v251, 7
	v_readlane_b32 s38, v251, 8
	v_readlane_b32 s39, v251, 9
	v_readlane_b32 s40, v251, 10
	v_readlane_b32 s41, v251, 11
	v_readlane_b32 s42, v251, 12
	v_readlane_b32 s43, v251, 13
	v_readlane_b32 s44, v251, 14
	v_readlane_b32 s45, v251, 15
	v_readlane_b32 s46, v251, 16
	v_readlane_b32 s47, v251, 17
	s_cbranch_vccnz .LBB0_653
	s_and_saveexec_b64 s[4:5], s[2:3]
	s_cbranch_execz .LBB0_607
	v_readfirstlane_b32 s98, v254
	s_cmpk_gt_u32 s98, 2
	s_cbranch_scc1 .LBB0_606
	v_readfirstlane_b32 s98, v255
	s_cmpk_gt_u32 s98, 3
	s_cbranch_scc1 .LBB0_606
	s_memrealtime s[18:19]
	v_mov_b32_e32 v4, 0
	v_mov_b64_e32 v[2:3], 0x1e8481
	s_branch .LBB0_599

.LBB0_633:
	s_mov_b64 s[100:101], exec
	v_readlane_b32 s98, v251, 41
	v_readlane_b32 s99, v251, 42
	s_and_b64 s[98:99], s[100:101], s[98:99]
	s_mov_b64 exec, s[98:99]
	s_cbranch_execz .Lmy_pm4_skip
	v_readlane_b32 s98, v251, 62
	v_readlane_b32 s99, v251, 61
	s_lshl_b32 s98, s98, 3
	s_and_b32 s99, s99, 7
	s_or_b32 s98, s98, s99
	s_lshl_b32 s98, s98, 8
	v_mov_b32_e32 v252, s98
	v_readlane_b32 s98, v251, 20
	v_readlane_b32 s99, v251, 21
	s_add_u32 s98, s98, 0x1c000
	s_addc_u32 s99, s99, 0
	global_load_dword v254, v252, s[98:99] sc1
	v_mov_b32_e32 v255, 0

.LBB0_649:
	s_or_b64 exec, exec, s[4:5]
	s_and_b32 s2, s1, 64
	v_readfirstlane_b32 s3, v0
	v_or_b32_e32 v8, s2, v189
	v_mov_b32_e32 v3, 0
	s_lshr_b32 s3, s3, 6
	v_lshlrev_b32_e32 v8, 11, v8
	v_mov_b32_e32 v9, v3
	s_lshl_b32 s4, s3, 8
	s_mov_b32 s5, 0
	v_lshl_add_u64 v[8:9], s[12:13], 0, v[8:9]
	s_and_b32 s1, s70, 63
	v_readlane_b32 s14, v251, 45
	v_and_b32_e32 v2, 48, v0
	v_lshl_add_u64 v[8:9], v[8:9], 0, s[4:5]
	s_add_u32 s14, s14, s4
	v_lshl_add_u64 v[106:107], v[8:9], 0, v[2:3]
	s_mov_b32 s4, 0x8000
	v_add_co_u32_e32 v108, vcc, s4, v106
	s_mov_b32 s12, 0x10000
	s_nop 0
	v_addc_co_u32_e32 v109, vcc, 0, v107, vcc
	v_readlane_b32 s15, v251, 46
	v_add_co_u32_e32 v110, vcc, s12, v106
	s_addc_u32 s15, s15, 0
	v_lshlrev_b32_e32 v6, 11, v189
	s_mov_b32 s13, 0x18000
	v_addc_co_u32_e32 v111, vcc, 0, v107, vcc
	v_lshl_add_u64 v[4:5], s[14:15], 0, v[2:3]
	v_lshl_or_b32 v6, s1, 17, v6
	v_mov_b32_e32 v7, v3
	v_add_co_u32_e32 v112, vcc, s13, v106
	v_lshl_add_u64 v[104:105], v[4:5], 0, v[6:7]
	s_nop 0
	v_addc_co_u32_e32 v113, vcc, 0, v107, vcc
	v_add_co_u32_e32 v114, vcc, s4, v104
	s_nop 1
	v_addc_co_u32_e32 v115, vcc, 0, v105, vcc
	v_add_co_u32_e32 v116, vcc, s12, v104
	s_barrier
	s_nop 0
	v_addc_co_u32_e32 v117, vcc, 0, v105, vcc
	v_add_co_u32_e32 v120, vcc, s13, v104
	s_nop 1
	v_addc_co_u32_e32 v121, vcc, 0, v105, vcc
	global_load_dwordx4 v[4:7], v[104:105], off
	global_load_dwordx4 v[8:11], v[106:107], off
	global_load_dwordx4 v[12:15], v[108:109], off
	global_load_dwordx4 v[16:19], v[106:107], off offset:64
	global_load_dwordx4 v[20:23], v[110:111], off
	global_load_dwordx4 v[24:27], v[104:105], off offset:64
	global_load_dwordx4 v[32:35], v[108:109], off offset:64
	global_load_dwordx4 v[40:43], v[112:113], off
	global_load_dwordx4 v[44:47], v[110:111], off offset:64
	global_load_dwordx4 v[52:55], v[112:113], off offset:64
	global_load_dwordx4 v[56:59], v[114:115], off
	global_load_dwordx4 v[60:63], v[114:115], off offset:64
	global_load_dwordx4 v[76:79], v[116:117], off
	global_load_dwordx4 v[80:83], v[116:117], off offset:64
	global_load_dwordx4 v[96:99], v[120:121], off
	global_load_dwordx4 v[100:103], v[120:121], off offset:64
	s_mulk_i32 s3, 0x4400
	s_add_i32 s3, s3, 0
	v_readlane_b32 s36, v251, 6
	v_readlane_b32 s50, v251, 20
	v_readlane_b32 s51, v251, 21
	s_lshl_b32 s4, s1, 7
	s_movk_i32 s1, 0x7fff
	v_readlane_b32 s37, v251, 7
	v_readlane_b32 s38, v251, 8
	v_readlane_b32 s39, v251, 9
	v_readlane_b32 s40, v251, 10
	v_readlane_b32 s41, v251, 11
	v_readlane_b32 s42, v251, 12
	v_readlane_b32 s43, v251, 13
	v_readlane_b32 s44, v251, 14
	v_readlane_b32 s45, v251, 15
	v_readlane_b32 s46, v251, 16
	v_readlane_b32 s47, v251, 17
	v_readlane_b32 s48, v251, 18
	v_readlane_b32 s49, v251, 19
	s_waitcnt vmcnt(14)
	v_mfma_f32_16x16x32_bf16 v[28:31], v[4:7], v[8:11], 0
	s_waitcnt vmcnt(13)
	v_mfma_f32_16x16x32_bf16 v[36:39], v[4:7], v[12:15], 0
	s_waitcnt vmcnt(11)
	v_mfma_f32_16x16x32_bf16 v[48:51], v[4:7], v[20:23], 0
	s_waitcnt vmcnt(8)
	v_mfma_f32_16x16x32_bf16 v[4:7], v[4:7], v[40:43], 0
	s_waitcnt vmcnt(5)
	v_mfma_f32_16x16x32_bf16 v[64:67], v[56:59], v[8:11], 0
	v_mfma_f32_16x16x32_bf16 v[68:71], v[56:59], v[12:15], 0
	v_mfma_f32_16x16x32_bf16 v[72:75], v[56:59], v[20:23], 0
	v_mfma_f32_16x16x32_bf16 v[56:59], v[56:59], v[40:43], 0
	s_waitcnt vmcnt(3)
	v_mfma_f32_16x16x32_bf16 v[84:87], v[76:79], v[8:11], 0
	v_mfma_f32_16x16x32_bf16 v[92:95], v[76:79], v[20:23], 0
	s_waitcnt vmcnt(1)
	v_mfma_f32_16x16x32_bf16 v[8:11], v[96:99], v[8:11], 0
	v_mfma_f32_16x16x32_bf16 v[20:23], v[96:99], v[20:23], 0
	v_mfma_f32_16x16x32_bf16 v[28:31], v[24:27], v[16:19], v[28:31]
	v_mfma_f32_16x16x32_bf16 v[36:39], v[24:27], v[32:35], v[36:39]
	v_mfma_f32_16x16x32_bf16 v[48:51], v[24:27], v[44:47], v[48:51]
	v_mfma_f32_16x16x32_bf16 v[4:7], v[24:27], v[52:55], v[4:7]
	v_mfma_f32_16x16x32_bf16 v[24:27], v[60:63], v[16:19], v[64:67]
	v_mfma_f32_16x16x32_bf16 v[64:67], v[60:63], v[32:35], v[68:71]
	v_mfma_f32_16x16x32_bf16 v[68:71], v[60:63], v[44:47], v[72:75]
	v_mfma_f32_16x16x32_bf16 v[56:59], v[60:63], v[52:55], v[56:59]
	v_mfma_f32_16x16x32_bf16 v[60:63], v[80:83], v[16:19], v[84:87]
	s_waitcnt vmcnt(0)
	v_mfma_f32_16x16x32_bf16 v[8:11], v[100:103], v[16:19], v[8:11]
	v_mfma_f32_16x16x32_bf16 v[16:19], v[100:103], v[44:47], v[20:23]
	s_nop 2
	global_load_dwordx4 v[20:23], v[104:105], off offset:128
	v_mfma_f32_16x16x32_bf16 v[88:91], v[76:79], v[12:15], 0
	v_mfma_f32_16x16x32_bf16 v[76:79], v[76:79], v[40:43], 0
	v_mfma_f32_16x16x32_bf16 v[12:15], v[96:99], v[12:15], 0
	v_mfma_f32_16x16x32_bf16 v[40:43], v[96:99], v[40:43], 0
	v_mfma_f32_16x16x32_bf16 v[72:75], v[80:83], v[32:35], v[88:91]
	v_mfma_f32_16x16x32_bf16 v[84:87], v[80:83], v[44:47], v[92:95]
	v_mfma_f32_16x16x32_bf16 v[76:79], v[80:83], v[52:55], v[76:79]
	v_mfma_f32_16x16x32_bf16 v[12:15], v[100:103], v[32:35], v[12:15]
	v_mfma_f32_16x16x32_bf16 v[32:35], v[100:103], v[52:55], v[40:43]
	s_nop 2
	global_load_dwordx4 v[40:43], v[106:107], off offset:128
	global_load_dwordx4 v[44:47], v[106:107], off offset:192
	global_load_dwordx4 v[52:55], v[104:105], off offset:192
	global_load_dwordx4 v[80:83], v[108:109], off offset:128
	global_load_dwordx4 v[88:91], v[108:109], off offset:192
	global_load_dwordx4 v[92:95], v[110:111], off offset:128
	global_load_dwordx4 v[96:99], v[110:111], off offset:192
	global_load_dwordx4 v[100:103], v[112:113], off offset:128
	global_load_dwordx4 v[104:107], v[112:113], off offset:192
	s_waitcnt vmcnt(8)
	v_mfma_f32_16x16x32_bf16 v[28:31], v[20:23], v[40:43], v[28:31]
	s_waitcnt vmcnt(5)
	v_mfma_f32_16x16x32_bf16 v[36:39], v[20:23], v[80:83], v[36:39]
	s_waitcnt vmcnt(3)
	v_mfma_f32_16x16x32_bf16 v[48:51], v[20:23], v[92:95], v[48:51]
	s_waitcnt vmcnt(1)
	v_mfma_f32_16x16x32_bf16 v[4:7], v[20:23], v[100:103], v[4:7]
	global_load_dwordx4 v[20:23], v[114:115], off offset:128
	global_load_dwordx4 v[108:111], v[114:115], off offset:192
	s_waitcnt vmcnt(1)
	v_mfma_f32_16x16x32_bf16 v[24:27], v[20:23], v[40:43], v[24:27]
	v_mfma_f32_16x16x32_bf16 v[64:67], v[20:23], v[80:83], v[64:67]
	v_mfma_f32_16x16x32_bf16 v[68:71], v[20:23], v[92:95], v[68:71]
	v_mfma_f32_16x16x32_bf16 v[20:23], v[20:23], v[100:103], v[56:59]
	s_nop 2
	global_load_dwordx4 v[56:59], v[116:117], off offset:128
	global_load_dwordx4 v[112:115], v[116:117], off offset:192
	s_nop 0
	global_load_dwordx4 v[116:119], v[120:121], off offset:128
	s_waitcnt vmcnt(2)
	v_mfma_f32_16x16x32_bf16 v[60:63], v[56:59], v[40:43], v[60:63]
	v_mfma_f32_16x16x32_bf16 v[72:75], v[56:59], v[80:83], v[72:75]
	v_mfma_f32_16x16x32_bf16 v[84:87], v[56:59], v[92:95], v[84:87]
	v_mfma_f32_16x16x32_bf16 v[56:59], v[56:59], v[100:103], v[76:79]
	s_nop 2
	global_load_dwordx4 v[76:79], v[120:121], off offset:192
	s_waitcnt vmcnt(1)
	v_mfma_f32_16x16x32_bf16 v[8:11], v[116:119], v[40:43], v[8:11]
	v_mfma_f32_16x16x32_bf16 v[28:31], v[52:55], v[44:47], v[28:31]
	v_mfma_f32_16x16x32_bf16 v[4:7], v[52:55], v[104:107], v[4:7]
	v_mfma_f32_16x16x32_bf16 v[12:15], v[116:119], v[80:83], v[12:15]
	v_mfma_f32_16x16x32_bf16 v[36:39], v[52:55], v[88:91], v[36:39]
	v_mfma_f32_16x16x32_bf16 v[24:27], v[108:111], v[44:47], v[24:27]
	v_mfma_f32_16x16x32_bf16 v[16:19], v[116:119], v[92:95], v[16:19]
	v_mfma_f32_16x16x32_bf16 v[40:43], v[52:55], v[96:99], v[48:51]
	v_mfma_f32_16x16x32_bf16 v[48:51], v[108:111], v[88:91], v[64:67]
	v_mfma_f32_16x16x32_bf16 v[52:55], v[108:111], v[96:99], v[68:71]
	s_nop 2
	v_mul_u32_u24_e32 v68, 0x110, v189
	v_add3_u32 v2, s3, v2, v68
	v_mfma_f32_16x16x32_bf16 v[32:35], v[116:119], v[100:103], v[32:35]
	ds_write_b128 v2, v[28:31]
	ds_write_b128 v2, v[36:39] offset:4352
	ds_write_b128 v2, v[40:43] offset:8704
	ds_write_b128 v2, v[4:7] offset:13056
	ds_write_b128 v2, v[24:27] offset:64
	ds_write_b128 v2, v[48:51] offset:4416
	v_mfma_f32_16x16x32_bf16 v[64:67], v[112:115], v[88:91], v[72:75]
	s_waitcnt vmcnt(0)
	v_mfma_f32_16x16x32_bf16 v[4:7], v[76:79], v[44:47], v[8:11]
	v_mfma_f32_16x16x32_bf16 v[20:23], v[108:111], v[104:107], v[20:23]
	v_mfma_f32_16x16x32_bf16 v[68:71], v[112:115], v[96:99], v[84:87]
	v_mfma_f32_16x16x32_bf16 v[8:11], v[76:79], v[88:91], v[12:15]
	s_nop 1
	v_and_b32_e32 v84, 7, v0
	v_or_b32_e32 v85, s2, v148
	s_mov_b32 s2, 0xf800000
	v_mfma_f32_16x16x32_bf16 v[60:63], v[112:115], v[44:47], v[60:63]
	ds_write_b128 v2, v[52:55] offset:8768
	ds_write_b128 v2, v[20:23] offset:13120
	s_nop 5
	ds_write_b128 v2, v[60:63] offset:128
	v_mfma_f32_16x16x32_bf16 v[28:31], v[112:115], v[104:107], v[56:59]
	ds_write_b128 v2, v[64:67] offset:4480
	ds_write_b128 v2, v[68:71] offset:8832
	s_nop 5
	ds_write_b128 v2, v[28:31] offset:13184
	v_mfma_f32_16x16x32_bf16 v[12:15], v[76:79], v[96:99], v[16:19]
	ds_write_b128 v2, v[4:7] offset:192
	ds_write_b128 v2, v[8:11] offset:4544
	s_nop 5
	ds_write_b128 v2, v[12:15] offset:8896
	v_mfma_f32_16x16x32_bf16 v[4:7], v[76:79], v[104:107], v[32:35]
	v_lshlrev_b32_e32 v76, 8, v85
	s_nop 6
	ds_write_b128 v2, v[4:7] offset:13248
	v_mul_u32_u24_e32 v2, 0x110, v148
	v_lshlrev_b32_e32 v4, 5, v84
	v_add3_u32 v2, 0, v2, v4
	s_waitcnt lgkmcnt(0)
	s_barrier
	ds_read_b128 v[4:7], v2
	ds_read_b128 v[8:11], v2 offset:16
	ds_read_b128 v[12:15], v2 offset:17408
	ds_read_b128 v[16:19], v2 offset:17424
	s_waitcnt lgkmcnt(3)
	v_add_f32_e32 v4, 0, v4
	s_waitcnt lgkmcnt(2)
	v_add_f32_e32 v8, 0, v8
	v_add_f32_e32 v5, 0, v5
	v_add_f32_e32 v9, 0, v9
	v_add_f32_e32 v6, 0, v6
	v_add_f32_e32 v24, 0, v10
	v_add_f32_e32 v25, 0, v7
	v_add_f32_e32 v26, 0, v11
	s_waitcnt lgkmcnt(1)
	v_add_f32_e32 v27, v4, v12
	s_waitcnt lgkmcnt(0)
	v_add_f32_e32 v28, v8, v16
	v_add_f32_e32 v29, v5, v13
	v_add_f32_e32 v30, v9, v17
	v_add_f32_e32 v31, v6, v14
	global_load_dwordx4 v[4:7], v76, s[10:11] offset:16
	global_load_dwordx4 v[8:11], v76, s[10:11]
	ds_read_b128 v[20:23], v2 offset:34816
	v_add_f32_e32 v44, v24, v18
	v_add_f32_e32 v45, v25, v15
	ds_read_b128 v[12:15], v2 offset:34832
	v_add_f32_e32 v46, v26, v19
	s_waitcnt lgkmcnt(1)
	v_add_f32_e32 v20, v27, v20
	global_load_dwordx4 v[16:19], v76, s[10:11] offset:48
	global_load_dwordx4 v[24:27], v76, s[10:11] offset:32
	v_add_f32_e32 v21, v29, v21
	s_waitcnt lgkmcnt(0)
	v_add_f32_e32 v12, v28, v12
	v_add_f32_e32 v47, v30, v13
	v_add_f32_e32 v48, v31, v22
	ds_read_b128 v[28:31], v2 offset:52224
	ds_read_b128 v[32:35], v2 offset:52240
	global_load_dwordx4 v[36:39], v76, s[10:11] offset:80
	global_load_dwordx4 v[40:43], v76, s[10:11] offset:64
	v_add_f32_e32 v60, v44, v14
	v_add_f32_e32 v61, v45, v23
	v_add_f32_e32 v62, v46, v15
	s_waitcnt lgkmcnt(1)
	v_add_f32_e32 v28, v20, v28
	s_waitcnt lgkmcnt(0)
	v_add_f32_e32 v32, v12, v32
	v_add_f32_e32 v29, v21, v29
	global_load_dwordx4 v[12:15], v76, s[10:11] offset:112
	global_load_dwordx4 v[20:23], v76, s[10:11] offset:96
	v_add_f32_e32 v64, v48, v30
	v_add_u32_e32 v30, 0x11000, v2
	v_add_f32_e32 v63, v47, v33
	v_add_u32_e32 v33, 0x11010, v2
	ds_read_b128 v[44:47], v30
	ds_read_b128 v[48:51], v33
	global_load_dwordx4 v[52:55], v76, s[10:11] offset:144
	global_load_dwordx4 v[56:59], v76, s[10:11] offset:128
	v_add_f32_e32 v77, v60, v34
	v_add_f32_e32 v78, v61, v31
	v_add_f32_e32 v79, v62, v35
	s_waitcnt lgkmcnt(1)
	v_add_f32_e32 v44, v28, v44
	s_waitcnt lgkmcnt(0)
	v_add_f32_e32 v48, v32, v48
	v_add_f32_e32 v45, v29, v45
	global_load_dwordx4 v[28:31], v76, s[10:11] offset:176
	global_load_dwordx4 v[32:35], v76, s[10:11] offset:160
	v_add_f32_e32 v81, v64, v46
	v_add_u32_e32 v46, 0x15400, v2
	v_add_f32_e32 v80, v63, v49
	v_add_u32_e32 v49, 0x15410, v2
	ds_read_b128 v[60:63], v46
	ds_read_b128 v[64:67], v49
	global_load_dwordx4 v[68:71], v76, s[10:11] offset:208
	global_load_dwordx4 v[72:75], v76, s[10:11] offset:192
	v_add_f32_e32 v86, v77, v50
	v_add_f32_e32 v87, v78, v47
	v_add_f32_e32 v88, v79, v51
	s_waitcnt lgkmcnt(1)
	v_add_f32_e32 v60, v44, v60
	s_waitcnt lgkmcnt(0)
	v_add_f32_e32 v64, v48, v64
	v_add_f32_e32 v61, v45, v61
	global_load_dwordx4 v[44:47], v76, s[10:11] offset:240
	global_load_dwordx4 v[48:51], v76, s[10:11] offset:224
	v_add_f32_e32 v65, v80, v65
	v_add_u32_e32 v76, 0x19800, v2
	v_add_u32_e32 v80, 0x19810, v2
	v_add_f32_e32 v62, v81, v62
	ds_read_b128 v[76:79], v76
	ds_read_b128 v[80:83], v80
	v_add_f32_e32 v86, v86, v66
	v_add_f32_e32 v87, v87, v63
	v_add_f32_e32 v88, v88, v67
	s_waitcnt lgkmcnt(1)
	v_add_f32_e32 v76, v60, v76
	v_add_u32_e32 v60, 0x1dc00, v2
	s_waitcnt lgkmcnt(0)
	v_add_f32_e32 v80, v64, v80
	v_add_f32_e32 v77, v61, v77
	v_add_f32_e32 v81, v65, v81
	v_add_f32_e32 v78, v62, v78
	v_add_u32_e32 v2, 0x1dc10, v2
	ds_read_b128 v[60:63], v60
	ds_read_b128 v[64:67], v2
	v_add_f32_e32 v2, v86, v82
	v_add_f32_e32 v79, v87, v79
	v_add_f32_e32 v82, v88, v83
	s_waitcnt lgkmcnt(1)
	v_add_f32_e32 v60, v76, v60
	s_waitcnt lgkmcnt(0)
	v_add_f32_e32 v2, v2, v66
	v_add_f32_e32 v64, v80, v64
	s_waitcnt vmcnt(14)
	v_add_f32_e32 v8, 0, v8
	v_add_f32_e32 v8, v8, v9
	v_add_f32_e32 v8, v8, v10
	v_add_f32_e32 v8, v8, v11
	v_add_f32_e32 v4, v8, v4
	v_add_f32_e32 v4, v4, v5
	v_add_f32_e32 v4, v4, v6
	v_add_f32_e32 v4, v4, v7
	s_waitcnt vmcnt(12)
	v_add_f32_e32 v4, v4, v24
	v_add_f32_e32 v4, v4, v25
	v_add_f32_e32 v4, v4, v26
	v_add_f32_e32 v4, v4, v27
	v_add_f32_e32 v4, v4, v16
	v_add_f32_e32 v4, v4, v17
	v_add_f32_e32 v4, v4, v18
	v_add_f32_e32 v4, v4, v19
	s_waitcnt vmcnt(10)
	v_add_f32_e32 v4, v4, v40
	v_add_f32_e32 v4, v4, v41
	v_add_f32_e32 v4, v4, v42
	v_add_f32_e32 v4, v4, v43
	v_add_f32_e32 v4, v4, v36
	v_add_f32_e32 v4, v4, v37
	v_add_f32_e32 v4, v4, v38
	v_add_f32_e32 v4, v4, v39
	s_waitcnt vmcnt(8)
	v_add_f32_e32 v4, v4, v20
	v_add_f32_e32 v4, v4, v21
	v_add_f32_e32 v4, v4, v22
	v_add_f32_e32 v4, v4, v23
	v_add_f32_e32 v4, v4, v12
	v_add_f32_e32 v4, v4, v13
	v_add_f32_e32 v4, v4, v14
	v_add_f32_e32 v4, v4, v15
	s_waitcnt vmcnt(6)
	v_add_f32_e32 v4, v4, v56
	v_add_f32_e32 v4, v4, v57
	v_add_f32_e32 v4, v4, v58
	v_add_f32_e32 v4, v4, v59
	v_add_f32_e32 v4, v4, v52
	v_add_f32_e32 v4, v4, v53
	v_add_f32_e32 v4, v4, v54
	v_add_f32_e32 v4, v4, v55
	s_waitcnt vmcnt(4)
	v_add_f32_e32 v4, v4, v32
	v_add_f32_e32 v4, v4, v33
	v_add_f32_e32 v4, v4, v34
	v_add_f32_e32 v4, v4, v35
	v_add_f32_e32 v4, v4, v28
	v_add_f32_e32 v4, v4, v29
	v_add_f32_e32 v4, v4, v30
	v_add_f32_e32 v4, v4, v31
	s_waitcnt vmcnt(2)
	v_add_f32_e32 v4, v4, v72
	v_add_f32_e32 v4, v4, v73
	v_add_f32_e32 v4, v4, v74
	v_add_f32_e32 v4, v4, v75
	v_add_f32_e32 v4, v4, v68
	v_add_f32_e32 v4, v4, v69
	v_add_f32_e32 v4, v4, v70
	v_add_f32_e32 v4, v4, v71
	s_waitcnt vmcnt(0)
	v_add_f32_e32 v4, v4, v48
	v_add_f32_e32 v4, v4, v49
	v_add_f32_e32 v4, v4, v50
	v_add_f32_e32 v4, v4, v51
	v_add_f32_e32 v4, v4, v44
	v_add_f32_e32 v4, v4, v45
	v_add_f32_e32 v4, v4, v46
	v_add_f32_e32 v4, v4, v47
	v_mov_b32_e32 v5, 0x358637bd
	v_fmac_f32_e32 v5, 0x3a800000, v4
	v_mul_f32_e32 v4, 0x4f800000, v5
	v_cmp_gt_f32_e32 vcc, s2, v5
	v_add_f32_e32 v6, v77, v61
	v_add_f32_e32 v9, v81, v65
	v_cndmask_b32_e32 v4, v5, v4, vcc
	v_sqrt_f32_e32 v5, v4
	v_add_f32_e32 v7, v78, v62
	v_add_f32_e32 v11, v82, v67
	v_add_u32_e32 v8, -1, v5
	v_fma_f32 v10, -v8, v5, v4
	v_cmp_ge_f32_e64 s[2:3], 0, v10
	v_add_u32_e32 v10, 1, v5
	s_nop 0
	v_cndmask_b32_e64 v8, v5, v8, s[2:3]
	v_fma_f32 v5, -v10, v5, v4
	v_cmp_lt_f32_e64 s[2:3], 0, v5
	s_nop 1
	v_cndmask_b32_e64 v5, v8, v10, s[2:3]
	v_mul_f32_e32 v8, 0x37800000, v5
	v_cndmask_b32_e32 v5, v5, v8, vcc
	v_mov_b32_e32 v8, 0x260
	v_cmp_class_f32_e32 vcc, v4, v8
	v_add_f32_e32 v10, v79, v63
	s_nop 0
	v_cndmask_b32_e32 v4, v5, v4, vcc
	v_div_scale_f32 v5, s[2:3], v4, v4, 1.0
	v_rcp_f32_e32 v8, v5
	s_mov_b64 s[2:3], 0x2f00000
	v_fma_f32 v12, -v5, v8, 1.0
	v_fmac_f32_e32 v8, v12, v8
	v_div_scale_f32 v12, vcc, 1.0, v4, 1.0
	v_mul_f32_e32 v13, v12, v8
	v_fma_f32 v14, -v5, v13, v12
	v_fmac_f32_e32 v13, v14, v8
	v_fma_f32 v5, -v5, v13, v12
	v_div_fmas_f32 v5, v5, v8, v13
	v_div_fixup_f32 v12, v5, v4, 1.0
	v_mul_f32_e32 v5, v6, v12
	v_mul_f32_e32 v9, v9, v12
	v_mul_f32_e32 v2, v2, v12
	v_max_f32_e32 v6, 0, v5
	v_mul_f32_e32 v5, v7, v12
	v_mul_f32_e32 v7, v10, v12
	v_max_f32_e32 v10, 0, v9
	v_max_f32_e32 v9, 0, v2
	v_mul_f32_e32 v2, v11, v12
	v_max_f32_e32 v11, 0, v2
	v_lshlrev_b32_e32 v2, 13, v85
	v_mul_f32_e32 v4, v60, v12
	v_mul_f32_e32 v8, v64, v12
	v_lshl_add_u64 v[12:13], s[50:51], 0, v[2:3]
	v_lshl_add_u64 v[12:13], v[12:13], 0, s[4:5]
	v_lshlrev_b32_e32 v2, 4, v84
	v_max_f32_e32 v4, 0, v4
	v_max_f32_e32 v5, 0, v5
	v_max_f32_e32 v7, 0, v7
	v_max_f32_e32 v8, 0, v8
	v_lshl_add_u64 v[2:3], v[12:13], 0, v[2:3]
	v_lshl_add_u64 v[12:13], v[2:3], 0, s[2:3]
	v_pk_mul_f32 v[2:3], v[4:5], v[4:5]
	v_pk_mul_f32 v[4:5], v[6:7], v[6:7]
	v_pk_mul_f32 v[6:7], v[8:9], v[8:9]
	v_pk_mul_f32 v[8:9], v[10:11], v[10:11]
	v_bfe_u32 v14, v5, 16, 1
	v_bfe_u32 v10, v9, 16, 1
	v_bfe_u32 v11, v8, 16, 1
	v_bfe_u32 v15, v4, 16, 1
	v_add3_u32 v15, v4, v15, s1
	v_add3_u32 v14, v5, v14, s1
	v_add3_u32 v4, v8, v11, s1
	v_add3_u32 v5, v9, v10, s1
	v_bfe_u32 v8, v2, 16, 1
	v_bfe_u32 v9, v3, 16, 1
	v_bfe_u32 v10, v6, 16, 1
	v_bfe_u32 v11, v7, 16, 1
	v_add3_u32 v7, v7, v11, s1
	v_add3_u32 v6, v6, v10, s1
	v_add3_u32 v3, v3, v9, s1
	v_add3_u32 v2, v2, v8, s1
	v_lshrrev_b32_e32 v2, 16, v2
	v_lshrrev_b32_e32 v3, 16, v3
	v_lshrrev_b32_e32 v6, 16, v6
	v_lshrrev_b32_e32 v7, 16, v7
	s_mov_b32 s1, 0xffff0000
	v_and_or_b32 v5, v5, s1, v7
	v_and_or_b32 v4, v4, s1, v6
	v_and_or_b32 v3, v14, s1, v3
	v_and_or_b32 v2, v15, s1, v2
	global_store_dwordx4 v[12:13], v[2:5], off sc1
	s_nop 1
	s_barrier
	s_mov_b64 s[100:101], exec
	v_readlane_b32 s98, v251, 41
	v_readlane_b32 s99, v251, 42
	s_and_b64 s[98:99], s[100:101], s[98:99]
	s_mov_b64 exec, s[98:99]
	s_cbranch_execz .Lmy_pn4_skip
	v_readlane_b32 s98, v251, 62
	v_readlane_b32 s99, v251, 61
	s_lshl_b32 s98, s98, 3
	s_and_b32 s99, s99, 7
	s_or_b32 s98, s98, s99
	s_lshl_b32 s98, s98, 8
	v_mov_b32_e32 v252, s98
	v_readlane_b32 s98, v251, 20
	v_readlane_b32 s99, v251, 21
	s_add_u32 s98, s98, 0x1c000
	s_addc_u32 s99, s99, 0
	global_load_dword v255, v252, s[98:99] sc1
.Lmy_pn4_skip:
	s_mov_b64 exec, s[100:101]
	s_waitcnt vmcnt(0)
	s_barrier
	s_mov_b64 s[2:3], exec
	v_readlane_b32 s4, v251, 41
	v_readlane_b32 s5, v251, 42
	s_and_b64 s[4:5], s[2:3], s[4:5]
	s_mov_b64 exec, s[4:5]
	s_cbranch_execz .LBB0_652
	s_mov_b64 s[4:5], exec
	v_mbcnt_lo_u32_b32 v2, s4, 0
	v_mbcnt_hi_u32_b32 v2, s5, v2
	v_cmp_eq_u32_e32 vcc, 0, v2
	s_and_b64 s[10:11], exec, vcc
	s_mov_b64 exec, s[10:11]
	s_cbranch_execz .LBB0_652
	s_bcnt1_i32_b64 s1, s[4:5]
	v_mov_b32_e32 v2, 0
	v_mov_b32_e32 v3, s1
	global_atomic_add v2, v3, s[20:21]

.Lmy_t5b_skip:
	v_cmp_gt_u32_e64 s[2:3], 64, v0
	s_and_saveexec_b64 s[4:5], s[2:3]
	s_cbranch_execz .LBB0_666
	v_readfirstlane_b32 s98, v254
	s_cmpk_gt_u32 s98, 2
	s_cbranch_scc1 .LBB0_665
	v_readfirstlane_b32 s98, v255
	s_cmpk_gt_u32 s98, 3
	s_cbranch_scc1 .LBB0_665
	s_memrealtime s[6:7]
	v_mov_b32_e32 v4, 0
	v_mov_b64_e32 v[2:3], 0x1e8481
	s_branch .LBB0_658

.LBB0_707:
	s_mov_b64 s[100:101], exec
	v_readlane_b32 s98, v251, 41
	v_readlane_b32 s99, v251, 42
	s_and_b64 s[98:99], s[100:101], s[98:99]
	s_mov_b64 exec, s[98:99]
	s_cbranch_execz .Lmy_pm5_skip
	v_readlane_b32 s98, v251, 62
	v_readlane_b32 s99, v251, 61
	s_lshl_b32 s98, s98, 3
	s_and_b32 s99, s99, 7
	s_or_b32 s98, s98, s99
	s_lshl_b32 s98, s98, 8
	v_mov_b32_e32 v252, s98
	v_readlane_b32 s98, v251, 20
	v_readlane_b32 s99, v251, 21
	s_add_u32 s98, s98, 0x20000
	s_addc_u32 s99, s99, 0
	global_load_dword v254, v252, s[98:99] sc1
	v_mov_b32_e32 v255, 0

.LBB0_728:
	s_or_b64 exec, exec, s[6:7]
	s_barrier
	s_mov_b64 s[100:101], exec
	v_readlane_b32 s98, v251, 41
	v_readlane_b32 s99, v251, 42
	s_and_b64 s[98:99], s[100:101], s[98:99]
	s_mov_b64 exec, s[98:99]
	s_cbranch_execz .Lmy_pn5_skip
	v_readlane_b32 s98, v251, 62
	v_readlane_b32 s99, v251, 61
	s_lshl_b32 s98, s98, 3
	s_and_b32 s99, s99, 7
	s_or_b32 s98, s98, s99
	s_lshl_b32 s98, s98, 8
	v_mov_b32_e32 v252, s98
	v_readlane_b32 s98, v251, 20
	v_readlane_b32 s99, v251, 21
	s_add_u32 s98, s98, 0x20000
	s_addc_u32 s99, s99, 0
	global_load_dword v255, v252, s[98:99] sc1
.Lmy_pn5_skip:
	s_mov_b64 exec, s[100:101]
	s_waitcnt vmcnt(0)
	s_barrier
	s_mov_b64 s[2:3], exec
	v_readlane_b32 s4, v251, 41
	v_readlane_b32 s5, v251, 42
	s_and_b64 s[4:5], s[2:3], s[4:5]
	s_mov_b64 exec, s[4:5]
	s_cbranch_execz .LBB0_731
	s_mov_b64 s[4:5], exec
	v_mbcnt_lo_u32_b32 v2, s4, 0
	v_mbcnt_hi_u32_b32 v2, s5, v2
	v_cmp_eq_u32_e32 vcc, 0, v2
	s_and_b64 s[6:7], exec, vcc
	s_mov_b64 exec, s[6:7]
	s_cbranch_execz .LBB0_731
	s_bcnt1_i32_b64 s1, s[4:5]
	v_mov_b32_e32 v2, 0
	v_mov_b32_e32 v3, s1
	global_atomic_add v2, v3, s[16:17]
